# window attention tile loop: PV accumulators and next-tile P kept in place across the back-edge (no per-tile register copies); window prologue loads issued before the sink/score-bound wait; dense loop
# speedup vs baseline: 1.0243x; 1.0060x over previous
.LBB0_427:
	v_readlane_b32 s2, v254, 7
	s_lshl_b32 s1, s1, 8
	s_add_i32 s6, s0, s2
	s_and_b32 s7, s1, 0x700
	s_lshl_b32 s0, s0, 11
	v_readlane_b32 s1, v253, 40
	s_add_i32 s0, s0, s1
	s_or_b32 s4, s7, s0
	s_add_i32 s0, s8, s25
	v_readlane_b32 s76, v253, 4
	s_ashr_i32 s1, s0, 31
	v_readlane_b32 s80, v253, 8
	v_readlane_b32 s81, v253, 9
	s_ashr_i32 s2, s8, 2
	s_min_u32 s18, s7, 0x680
	s_lshl_b64 s[0:1], s[0:1], 2
	s_mov_b64 s[12:13], s[80:81]
	v_mov_b32_e32 v0, 0x80
	s_add_u32 s0, s12, s0
	v_sub_u32_e64 v0, s7, v0 clamp
	s_addc_u32 s1, s13, s1
	v_readfirstlane_b32 s28, v0
	global_load_dword v48, v1, s[0:1]
	s_mul_i32 s0, s6, 20
	s_ashr_i32 s1, s0, 31
	s_lshl_b64 s[0:1], s[0:1], 2
	s_add_u32 s5, s54, s0
	s_addc_u32 s10, s58, s1
	s_ashr_i32 s9, s8, 31
	s_lshl_b64 s[0:1], s[8:9], 2
	s_add_u32 s0, s5, s0
	s_addc_u32 s1, s10, s1
	s_ashr_i32 s3, s2, 31
	v_readlane_b32 s77, v253, 5
	v_readlane_b32 s80, v255, 3
	v_readlane_b32 s76, v255, 5
	v_readlane_b32 s81, v255, 4
	v_readlane_b32 s77, v255, 6
	v_readlane_b32 s78, v253, 6
	v_readlane_b32 s79, v253, 7
	v_readlane_b32 s82, v253, 10
	v_readlane_b32 s83, v253, 11
	global_load_dword v49, v1, s[0:1] sc1
	s_lshl_b64 s[0:1], s[2:3], 2
	s_add_u32 s0, s5, s0
	s_addc_u32 s1, s10, s1
	s_ashr_i32 s5, s4, 31
	s_lshl_b64 s[4:5], s[4:5], 11
	global_load_dword v50, v1, s[0:1] offset:64 sc1
	s_add_u32 s3, s36, s4
	s_addc_u32 s10, s37, s5
	s_lshl_b32 s8, s8, 6
	s_ashr_i32 s9, s8, 31
	s_lshl_b64 s[8:9], s[8:9], 1
	s_add_u32 s14, s3, s8
	s_addc_u32 s15, s10, s9
	s_mul_i32 s10, s6, 0x120000
	s_mul_hi_i32 s3, s6, 0x120000
	s_add_u32 s12, s38, s10
	s_addc_u32 s3, s39, s3
	s_lshl_b32 s10, s2, 6
	s_ashr_i32 s11, s10, 31
	s_lshl_b64 s[10:11], s[10:11], 1
	s_add_u32 s12, s12, s10
	s_addc_u32 s13, s3, s11
	s_lshl_b32 s3, s6, 2
	s_add_i32 s2, s3, s2
	s_mul_hi_i32 s3, s2, 0x48000
	s_mul_i32 s2, s2, 0x48000
	s_add_u32 s16, s57, s2
	s_addc_u32 s17, s88, s3
	s_add_u32 s2, s84, s4
	s_addc_u32 s3, s85, s5
	s_add_u32 s10, s2, s8
	s_addc_u32 s11, s3, s9
	s_sub_i32 s29, s18, s28
	s_addk_i32 s29, 0x180
	s_lshr_b32 s6, s28, 6
	s_ashr_i32 s27, s29, 6
	v_mov_b32_e32 v17, v209
	v_mov_b32_e32 v23, v1
	v_readfirstlane_b32 s0, v17
	s_ashr_i32 s0, s0, 1
	s_and_b32 s4, s0, 0xffffffe0
	s_add_i32 s20, s4, s7
	v_mov_b32_e32 v0, s0
	s_movk_i32 s0, 0xffe0
	s_cmp_gt_i32 s27, 0
	v_bfi_b32 v2, s0, v0, v17
	s_cselect_b64 s[0:1], -1, 0
	s_sub_i32 s5, 0x800, s29
	v_ashrrev_i32_e32 v3, 31, v2
	s_cmp_lt_i32 s27, 1
	v_bfe_u32 v226, v17, 5, 1
	v_lshlrev_b64 v[188:189], 11, v[2:3]
	s_cselect_b64 s[2:3], -1, 0
	v_lshl_add_u64 v[2:3], s[14:15], 0, v[188:189]
	v_lshlrev_b32_e32 v0, 4, v226
	s_and_b64 s[8:9], s[2:3], exec
	v_lshl_add_u64 v[14:15], v[2:3], 0, v[0:1]
	v_ashrrev_i32_e32 v194, 3, v17
	s_cselect_b32 s68, s5, s28
	global_load_dwordx4 v[2:5], v[14:15], off
	global_load_dwordx4 v[6:9], v[14:15], off offset:32
	global_load_dwordx4 v[10:13], v[14:15], off offset:64
	global_load_dwordx4 v[176:179], v[14:15], off offset:96
	v_add_u32_e32 v14, s68, v194
	v_ashrrev_i32_e32 v15, 31, v14
	v_and_b32_e32 v16, 7, v17
	v_lshlrev_b64 v[14:15], 9, v[14:15]
	s_or_b32 s5, s6, 1
	s_sub_i32 s8, 33, s27
	v_lshl_add_u64 v[14:15], s[12:13], 0, v[14:15]
	v_lshlrev_b32_e32 v22, 4, v16
	s_cmp_gt_i32 s27, 1
	v_lshl_add_u64 v[14:15], v[14:15], 0, v[22:23]
	s_cselect_b32 s5, s5, s8
	global_load_dwordx4 v[18:21], v[14:15], off
	v_lshl_add_u32 v14, s5, 6, v194
	v_ashrrev_i32_e32 v15, 31, v14
	v_lshlrev_b64 v[14:15], 9, v[14:15]
	v_lshl_add_u64 v[14:15], s[12:13], 0, v[14:15]
	v_lshl_add_u64 v[24:25], v[14:15], 0, v[22:23]
	v_mov_b64_e32 v[14:15], s[16:17]
	s_movk_i32 s5, 0x1200
	v_mad_i64_i32 v[14:15], s[8:9], v194, s5, v[14:15]
	v_lshl_add_u64 v[26:27], s[68:69], 1, v[14:15]
	v_lshl_add_u64 v[26:27], v[26:27], 0, v[22:23]
	global_load_dwordx4 v[180:183], v[26:27], off
	global_load_dwordx4 v[184:187], v[24:25], off
	s_waitcnt vmcnt(7)
	v_mul_f32_e32 v227, 0x3fb8aa3b, v48
	v_mul_f32_e32 v51, v49, v50
	s_mov_b32 s32, 0xf800000
	v_cmp_gt_f32_e32 vcc, s32, v51
	v_mul_f32_e32 v52, 0x4f800000, v51
	s_nop 0
	v_cndmask_b32_e32 v51, v51, v52, vcc
	v_sqrt_f32_e32 v52, v51
	s_nop 0
	v_add_u32_e32 v53, -1, v52
	v_fma_f32 v54, -v53, v52, v51
	v_cmp_ge_f32_e64 s[98:99], 0, v54
	v_add_u32_e32 v54, 1, v52
	s_nop 0
	v_cndmask_b32_e64 v53, v52, v53, s[98:99]
	v_fma_f32 v52, -v54, v52, v51
	v_cmp_lt_f32_e64 s[98:99], 0, v52
	s_nop 1
	v_cndmask_b32_e64 v52, v53, v54, s[98:99]
	v_mul_f32_e32 v53, 0x37800000, v52
	v_cndmask_b32_e32 v52, v52, v53, vcc
	v_mov_b32_e32 v53, 0x260
	v_cmp_class_f32_e32 vcc, v51, v53
	s_mov_b32 s32, 0x42480000
	s_nop 0
	v_cndmask_b32_e32 v51, v52, v51, vcc
	v_fmamk_f32 v51, v51, 0x3f828f5c, v214
	v_max_f32_e32 v51, v51, v227
	v_cmp_ge_f32_e32 vcc, s32, v51
	s_mov_b32 s32, 0xc2700000
	v_cmp_le_f32_e64 s[98:99], s32, v227
	s_and_b64 s[98:99], vcc, s[98:99]
	s_andn2_b64 vcc, exec, s[98:99]
	s_cbranch_vccz .Lwin_fx
	s_waitcnt vmcnt(0)
	s_mov_b64 s[2:3], -1
	v_mov_b32_e32 v18, v209
	v_mov_b32_e32 v21, v1
	v_readfirstlane_b32 s0, v18
	s_ashr_i32 s0, s0, 1
	s_and_b32 s4, s0, 0xffffffe0
	s_add_i32 s35, s4, s7
	v_mov_b32_e32 v0, s0
	s_movk_i32 s0, 0xffe0
	s_cmp_gt_i32 s27, 0
	v_bfi_b32 v2, s0, v0, v18
	s_cselect_b64 s[0:1], -1, 0
	s_sub_i32 s5, 0x800, s29
	v_ashrrev_i32_e32 v3, 31, v2
	s_cmp_lt_i32 s27, 1
	v_bfe_u32 v226, v18, 5, 1
	v_lshlrev_b64 v[14:15], 11, v[2:3]
	s_cselect_b64 s[2:3], -1, 0
	v_lshl_add_u64 v[2:3], s[14:15], 0, v[14:15]
	v_lshlrev_b32_e32 v0, 4, v226
	s_and_b64 s[8:9], s[2:3], exec
	v_lshl_add_u64 v[16:17], v[2:3], 0, v[0:1]
	v_ashrrev_i32_e32 v228, 3, v18
	s_cselect_b32 s68, s5, s28
	global_load_dwordx4 v[2:5], v[16:17], off
	global_load_dwordx4 v[6:9], v[16:17], off offset:32
	global_load_dwordx4 v[10:13], v[16:17], off offset:64
	global_load_dwordx4 v[192:195], v[16:17], off offset:96
	v_add_u32_e32 v16, s68, v228
	v_ashrrev_i32_e32 v17, 31, v16
	v_and_b32_e32 v35, 7, v18
	v_lshlrev_b64 v[16:17], 9, v[16:17]
	v_lshl_add_u64 v[16:17], s[12:13], 0, v[16:17]
	v_lshlrev_b32_e32 v20, 4, v35
	v_lshl_add_u64 v[16:17], v[16:17], 0, v[20:21]
	v_and_b32_e32 v34, 31, v18
	global_load_dwordx4 v[16:19], v[16:17], off
	s_movk_i32 s5, 0x90
	v_mul_lo_u32 v22, v228, s5
	s_or_b32 s5, s6, 1
	s_sub_i32 s8, 33, s27
	s_cmp_gt_i32 s27, 1
	v_add3_u32 v229, 0, v22, v20
	s_cselect_b32 s5, s5, s8
	s_add_i32 s30, s35, 0xffffff80
	v_cmp_eq_u32_e32 vcc, 0, v226
	v_xor_b32_e32 v80, 0x80000000, v227
	v_mov_b32_e32 v232, 1.0
	v_cndmask_b32_e64 v231, 0, 1.0, vcc
	v_mul_u32_u24_e32 v230, 0x90, v34
	v_lshl_add_u32 v100, s5, 6, v228
	v_ashrrev_i32_e32 v101, 31, v100
	v_lshlrev_b64 v[100:101], 9, v[100:101]
	v_lshl_add_u64 v[100:101], s[12:13], 0, v[100:101]
	v_lshl_add_u64 v[100:101], v[100:101], 0, v[20:21]
	global_load_dwordx4 v[196:199], v[100:101], off
	v_mov_b64_e32 v[100:101], s[16:17]
	s_movk_i32 s5, 0x1200
	v_mad_i64_i32 v[32:33], s[8:9], v228, s5, v[100:101]
	v_lshl_add_u64 v[100:101], s[68:69], 1, v[32:33]
	v_lshl_add_u64 v[100:101], v[100:101], 0, v[20:21]
	global_load_dwordx4 v[200:203], v[100:101], off
	s_waitcnt vmcnt(2)
	ds_write_b128 v229, v[16:19]
	s_or_b32 s5, s28, 63
	s_cmp_ge_i32 s5, s30
	s_cselect_b64 s[8:9], -1, 0
	s_add_i32 s31, s35, 0x9f
	s_cmp_le_i32 s28, s31
	s_cselect_b64 s[18:19], -1, 0
	s_and_b64 s[8:9], s[8:9], s[18:19]
	s_or_b64 s[8:9], s[2:3], s[8:9]
	s_andn2_b64 vcc, exec, s[8:9]
	s_waitcnt lgkmcnt(0)
	s_barrier
	s_cbranch_vccnz .LBB0_435
	v_add3_u32 v48, 0, v230, v0
	ds_read_b128 v[16:19], v48
	ds_read_b128 v[20:23], v48 offset:32
	ds_read_b128 v[24:27], v48 offset:4608
	ds_read_b128 v[28:31], v48 offset:4640
	ds_read_b128 v[36:39], v48 offset:64
	ds_read_b128 v[40:43], v48 offset:96
	ds_read_b128 v[44:47], v48 offset:4672
	ds_read_b128 v[96:99], v48 offset:4704
	v_mov_b32_e32 v81, v80
	v_mov_b32_e32 v82, v80
	v_mov_b32_e32 v83, v80
	v_mov_b32_e32 v84, v80
	v_mov_b32_e32 v85, v80
	v_mov_b32_e32 v86, v80
	v_mov_b32_e32 v87, v80
	v_mov_b32_e32 v88, v80
	v_mov_b32_e32 v89, v80
	v_mov_b32_e32 v90, v80
	v_mov_b32_e32 v91, v80
	v_mov_b32_e32 v92, v80
	v_mov_b32_e32 v93, v80
	v_mov_b32_e32 v94, v80
	v_mov_b32_e32 v95, v80
	v_mov_b64_e32 v[64:65], v[80:81]
	v_mov_b64_e32 v[66:67], v[82:83]
	v_mov_b64_e32 v[68:69], v[84:85]
	v_mov_b64_e32 v[70:71], v[86:87]
	v_mov_b64_e32 v[72:73], v[88:89]
	v_mov_b64_e32 v[74:75], v[90:91]
	v_mov_b64_e32 v[76:77], v[92:93]
	v_mov_b64_e32 v[78:79], v[94:95]
	s_waitcnt lgkmcnt(7)
	v_mfma_f32_32x32x16_bf16 v[48:63], v[16:19], v[2:5], v[80:95]
	s_andn2_b64 vcc, exec, s[0:1]
	s_waitcnt lgkmcnt(5)
	v_mfma_f32_32x32x16_bf16 v[64:79], v[24:27], v[2:5], v[64:79]
	v_mfma_f32_32x32x16_bf16 v[48:63], v[20:23], v[6:9], v[48:63]
	s_waitcnt lgkmcnt(4)
	v_mfma_f32_32x32x16_bf16 v[64:79], v[28:31], v[6:9], v[64:79]
	s_waitcnt lgkmcnt(3)
	v_mfma_f32_32x32x16_bf16 v[48:63], v[36:39], v[10:13], v[48:63]
	s_waitcnt lgkmcnt(1)
	v_mfma_f32_32x32x16_bf16 v[64:79], v[44:47], v[10:13], v[64:79]
	v_mfma_f32_32x32x16_bf16 v[48:63], v[40:43], v[192:195], v[48:63]
	s_waitcnt lgkmcnt(0)
	v_mfma_f32_32x32x16_bf16 v[64:79], v[96:99], v[192:195], v[64:79]
	s_cbranch_vccnz .LBB0_432
	s_add_i32 s0, s35, 0xffffff9f
	s_cmp_lt_i32 s28, s0
	s_cselect_b64 s[0:1], -1, 0
	s_add_i32 s2, s35, 0x41
	s_cmp_gt_i32 s28, s2
	s_cselect_b64 s[2:3], -1, 0
	s_or_b64 s[0:1], s[0:1], s[2:3]
	s_andn2_b64 vcc, exec, s[0:1]
	s_cbranch_vccnz .LBB0_432
	v_or_b32_e32 v16, s35, v34
	v_lshl_or_b32 v17, v226, 2, s28
	v_sub_u32_e32 v16, v16, v17
	v_add_u32_e32 v17, 0x80, v16
	s_movk_i32 s0, 0x101
	v_cmp_gt_u32_e32 vcc, s0, v17
	v_add_u32_e32 v17, 0xffffff5f, v16
	s_movk_i32 s0, 0xfefe
	v_cndmask_b32_e32 v48, v216, v48, vcc
	v_cmp_lt_u32_e32 vcc, s0, v17
	v_add_u32_e32 v17, 0xffffff7e, v16
	s_nop 0
	v_cndmask_b32_e32 v64, v216, v64, vcc
	v_cmp_lt_u32_e32 vcc, s0, v17
	v_add_u32_e32 v17, 0xffffff5e, v16
	s_nop 0
	v_cndmask_b32_e32 v49, v216, v49, vcc
	v_cmp_lt_u32_e32 vcc, s0, v17
	v_add_u32_e32 v17, 0xffffff7d, v16
	s_nop 0
	v_cndmask_b32_e32 v65, v216, v65, vcc
	v_cmp_lt_u32_e32 vcc, s0, v17
	v_add_u32_e32 v17, 0xffffff5d, v16
	s_nop 0
	v_cndmask_b32_e32 v50, v216, v50, vcc
	v_cmp_lt_u32_e32 vcc, s0, v17
	v_add_u32_e32 v17, 0xffffff7c, v16
	s_nop 0
	v_cndmask_b32_e32 v66, v216, v66, vcc
	v_cmp_lt_u32_e32 vcc, s0, v17
	v_add_u32_e32 v17, 0xffffff5c, v16
	s_nop 0
	v_cndmask_b32_e32 v51, v216, v51, vcc
	v_cmp_lt_u32_e32 vcc, s0, v17
	v_add_u32_e32 v17, 0xffffff77, v16
	s_nop 0
	v_cndmask_b32_e32 v67, v216, v67, vcc
	v_cmp_lt_u32_e32 vcc, s0, v17
	v_add_u32_e32 v17, 0xffffff57, v16
	s_nop 0
	v_cndmask_b32_e32 v52, v216, v52, vcc
	v_cmp_lt_u32_e32 vcc, s0, v17
	v_add_u32_e32 v17, 0xffffff76, v16
	s_nop 0
	v_cndmask_b32_e32 v68, v216, v68, vcc
	v_cmp_lt_u32_e32 vcc, s0, v17
	v_add_u32_e32 v17, 0xffffff56, v16
	s_nop 0
	v_cndmask_b32_e32 v53, v216, v53, vcc
	v_cmp_lt_u32_e32 vcc, s0, v17
	v_add_u32_e32 v17, 0xffffff75, v16
	s_nop 0
	v_cndmask_b32_e32 v69, v216, v69, vcc
	v_cmp_lt_u32_e32 vcc, s0, v17
	v_add_u32_e32 v17, 0xffffff55, v16
	s_nop 0
	v_cndmask_b32_e32 v54, v216, v54, vcc
	v_cmp_lt_u32_e32 vcc, s0, v17
	v_add_u32_e32 v17, 0xffffff74, v16
	s_nop 0
	v_cndmask_b32_e32 v70, v216, v70, vcc
	v_cmp_lt_u32_e32 vcc, s0, v17
	v_add_u32_e32 v17, 0xffffff54, v16
	s_nop 0
	v_cndmask_b32_e32 v55, v216, v55, vcc
	v_cmp_lt_u32_e32 vcc, s0, v17
	v_add_u32_e32 v17, 0xffffff6f, v16
	s_nop 0
	v_cndmask_b32_e32 v71, v216, v71, vcc
	v_cmp_lt_u32_e32 vcc, s0, v17
	v_add_u32_e32 v17, 0xffffff4f, v16
	s_nop 0
	v_cndmask_b32_e32 v56, v216, v56, vcc
	v_cmp_lt_u32_e32 vcc, s0, v17
	v_add_u32_e32 v17, 0xffffff6e, v16
	s_nop 0
	v_cndmask_b32_e32 v72, v216, v72, vcc
	v_cmp_lt_u32_e32 vcc, s0, v17
	v_add_u32_e32 v17, 0xffffff4e, v16
	s_nop 0
	v_cndmask_b32_e32 v57, v216, v57, vcc
	v_cmp_lt_u32_e32 vcc, s0, v17
	v_add_u32_e32 v17, 0xffffff6d, v16
	s_nop 0
	v_cndmask_b32_e32 v73, v216, v73, vcc
	v_cmp_lt_u32_e32 vcc, s0, v17
	v_add_u32_e32 v17, 0xffffff4d, v16
	s_nop 0
	v_cndmask_b32_e32 v58, v216, v58, vcc
	v_cmp_lt_u32_e32 vcc, s0, v17
	v_add_u32_e32 v17, 0xffffff6c, v16
	s_nop 0
	v_cndmask_b32_e32 v74, v216, v74, vcc
	v_cmp_lt_u32_e32 vcc, s0, v17
	v_add_u32_e32 v17, 0xffffff4c, v16
	s_nop 0
	v_cndmask_b32_e32 v59, v216, v59, vcc
	v_cmp_lt_u32_e32 vcc, s0, v17
	v_add_u32_e32 v17, 0xffffff67, v16
	s_nop 0
	v_cndmask_b32_e32 v75, v216, v75, vcc
	v_cmp_lt_u32_e32 vcc, s0, v17
	v_add_u32_e32 v17, 0xffffff47, v16
	s_nop 0
	v_cndmask_b32_e32 v60, v216, v60, vcc
	v_cmp_lt_u32_e32 vcc, s0, v17
	v_add_u32_e32 v17, 0xffffff66, v16
	s_nop 0
	v_cndmask_b32_e32 v76, v216, v76, vcc
	v_cmp_lt_u32_e32 vcc, s0, v17
	v_add_u32_e32 v17, 0xffffff46, v16
	s_nop 0
	v_cndmask_b32_e32 v61, v216, v61, vcc
	v_cmp_lt_u32_e32 vcc, s0, v17
	v_add_u32_e32 v17, 0xffffff65, v16
	s_nop 0
	v_cndmask_b32_e32 v77, v216, v77, vcc
	v_cmp_lt_u32_e32 vcc, s0, v17
	v_add_u32_e32 v17, 0xffffff45, v16
	s_nop 0
	v_cndmask_b32_e32 v62, v216, v62, vcc
	v_cmp_lt_u32_e32 vcc, s0, v17
	v_add_u32_e32 v17, 0xffffff64, v16
	v_add_u32_e32 v16, 0xffffff44, v16
	v_cndmask_b32_e32 v78, v216, v78, vcc
	v_cmp_lt_u32_e32 vcc, s0, v17
	s_nop 1
	v_cndmask_b32_e32 v63, v216, v63, vcc
	v_cmp_lt_u32_e32 vcc, s0, v16
	s_nop 1
	v_cndmask_b32_e32 v79, v216, v79, vcc

.Lwin_fx:
	s_movk_i32 s5, 0x90
	v_mul_lo_u32 v23, v194, s5
	s_or_b32 s5, s28, 63
	s_add_i32 s16, s20, 0xffffff80
	s_cmp_ge_i32 s5, s16
	s_cselect_b64 s[8:9], -1, 0
	s_add_i32 s17, s20, 0x9f
	s_cmp_le_i32 s28, s17
	s_cselect_b64 s[14:15], -1, 0
	s_and_b64 s[8:9], s[8:9], s[14:15]
	v_and_b32_e32 v17, 31, v17
	s_or_b64 s[2:3], s[2:3], s[8:9]
	v_add3_u32 v195, 0, v23, v22
	s_andn2_b64 vcc, exec, s[2:3]
	s_waitcnt vmcnt(7)
	v_mul_u32_u24_e32 v196, 0x90, v17
	s_waitcnt vmcnt(2)
	ds_write_b128 v195, v[18:21]
	s_waitcnt lgkmcnt(0)
	s_barrier
	s_cbranch_vccnz .LBB0_487
	v_add3_u32 v22, 0, v196, v0
	ds_read_b128 v[18:21], v22
	s_andn2_b64 vcc, exec, s[0:1]
	s_waitcnt lgkmcnt(0)
	v_mfma_f32_32x32x16_bf16 v[48:63], v[18:21], v[2:5], 0
	ds_read_b128 v[18:21], v22 offset:4608
	s_waitcnt lgkmcnt(0)
	v_mfma_f32_32x32x16_bf16 v[64:79], v[18:21], v[2:5], 0
	ds_read_b128 v[18:21], v22 offset:32
	s_waitcnt lgkmcnt(0)
	v_mfma_f32_32x32x16_bf16 v[48:63], v[18:21], v[6:9], v[48:63]
	ds_read_b128 v[18:21], v22 offset:4640
	s_waitcnt lgkmcnt(0)
	v_mfma_f32_32x32x16_bf16 v[64:79], v[18:21], v[6:9], v[64:79]
	ds_read_b128 v[18:21], v22 offset:64
	s_waitcnt lgkmcnt(0)
	v_mfma_f32_32x32x16_bf16 v[48:63], v[18:21], v[10:13], v[48:63]
	ds_read_b128 v[18:21], v22 offset:4672
	s_waitcnt lgkmcnt(0)
	v_mfma_f32_32x32x16_bf16 v[64:79], v[18:21], v[10:13], v[64:79]
	ds_read_b128 v[18:21], v22 offset:96
	s_waitcnt lgkmcnt(0)
	v_mfma_f32_32x32x16_bf16 v[48:63], v[18:21], v[176:179], v[48:63]
	ds_read_b128 v[18:21], v22 offset:4704
	s_waitcnt lgkmcnt(0)
	v_mfma_f32_32x32x16_bf16 v[64:79], v[18:21], v[176:179], v[64:79]
	s_cbranch_vccnz .LBB0_486
	s_add_i32 s0, s20, 0xffffff9f
	s_cmp_lt_i32 s28, s0
	s_cselect_b64 s[0:1], -1, 0
	s_add_i32 s5, s20, 0x41
	s_cmp_gt_i32 s28, s5
	s_cselect_b64 s[8:9], -1, 0
	s_or_b64 s[0:1], s[0:1], s[8:9]
	s_andn2_b64 vcc, exec, s[0:1]
	s_cbranch_vccnz .LBB0_486
	v_or_b32_e32 v18, s20, v17
	v_lshl_or_b32 v19, v226, 2, s28
	v_sub_u32_e32 v18, v18, v19
	v_add_u32_e32 v19, 0x80, v18
	s_movk_i32 s0, 0x101
	v_cmp_gt_u32_e32 vcc, s0, v19
	v_add_u32_e32 v19, 0xffffff5f, v18
	s_movk_i32 s0, 0xfefe
	v_cndmask_b32_e32 v48, v216, v48, vcc
	v_cmp_lt_u32_e32 vcc, s0, v19
	v_add_u32_e32 v19, 0xffffff7e, v18
	s_nop 0
	v_cndmask_b32_e32 v64, v216, v64, vcc
	v_cmp_lt_u32_e32 vcc, s0, v19
	v_add_u32_e32 v19, 0xffffff5e, v18
	s_nop 0
	v_cndmask_b32_e32 v49, v216, v49, vcc
	v_cmp_lt_u32_e32 vcc, s0, v19
	v_add_u32_e32 v19, 0xffffff7d, v18
	s_nop 0
	v_cndmask_b32_e32 v65, v216, v65, vcc
	v_cmp_lt_u32_e32 vcc, s0, v19
	v_add_u32_e32 v19, 0xffffff5d, v18
	s_nop 0
	v_cndmask_b32_e32 v50, v216, v50, vcc
	v_cmp_lt_u32_e32 vcc, s0, v19
	v_add_u32_e32 v19, 0xffffff7c, v18
	s_nop 0
	v_cndmask_b32_e32 v66, v216, v66, vcc
	v_cmp_lt_u32_e32 vcc, s0, v19
	v_add_u32_e32 v19, 0xffffff5c, v18
	s_nop 0
	v_cndmask_b32_e32 v51, v216, v51, vcc
	v_cmp_lt_u32_e32 vcc, s0, v19
	v_add_u32_e32 v19, 0xffffff77, v18
	s_nop 0
	v_cndmask_b32_e32 v67, v216, v67, vcc
	v_cmp_lt_u32_e32 vcc, s0, v19
	v_add_u32_e32 v19, 0xffffff57, v18
	s_nop 0
	v_cndmask_b32_e32 v52, v216, v52, vcc
	v_cmp_lt_u32_e32 vcc, s0, v19
	v_add_u32_e32 v19, 0xffffff76, v18
	s_nop 0
	v_cndmask_b32_e32 v68, v216, v68, vcc
	v_cmp_lt_u32_e32 vcc, s0, v19
	v_add_u32_e32 v19, 0xffffff56, v18
	s_nop 0
	v_cndmask_b32_e32 v53, v216, v53, vcc
	v_cmp_lt_u32_e32 vcc, s0, v19
	v_add_u32_e32 v19, 0xffffff75, v18
	s_nop 0
	v_cndmask_b32_e32 v69, v216, v69, vcc
	v_cmp_lt_u32_e32 vcc, s0, v19
	v_add_u32_e32 v19, 0xffffff55, v18
	s_nop 0
	v_cndmask_b32_e32 v54, v216, v54, vcc
	v_cmp_lt_u32_e32 vcc, s0, v19
	v_add_u32_e32 v19, 0xffffff74, v18
	s_nop 0
	v_cndmask_b32_e32 v70, v216, v70, vcc
	v_cmp_lt_u32_e32 vcc, s0, v19
	v_add_u32_e32 v19, 0xffffff54, v18
	s_nop 0
	v_cndmask_b32_e32 v55, v216, v55, vcc
	v_cmp_lt_u32_e32 vcc, s0, v19
	v_add_u32_e32 v19, 0xffffff6f, v18
	s_nop 0
	v_cndmask_b32_e32 v71, v216, v71, vcc
	v_cmp_lt_u32_e32 vcc, s0, v19
	v_add_u32_e32 v19, 0xffffff4f, v18
	s_nop 0
	v_cndmask_b32_e32 v56, v216, v56, vcc
	v_cmp_lt_u32_e32 vcc, s0, v19
	v_add_u32_e32 v19, 0xffffff6e, v18
	s_nop 0
	v_cndmask_b32_e32 v72, v216, v72, vcc
	v_cmp_lt_u32_e32 vcc, s0, v19
	v_add_u32_e32 v19, 0xffffff4e, v18
	s_nop 0
	v_cndmask_b32_e32 v57, v216, v57, vcc
	v_cmp_lt_u32_e32 vcc, s0, v19
	v_add_u32_e32 v19, 0xffffff6d, v18
	s_nop 0
	v_cndmask_b32_e32 v73, v216, v73, vcc
	v_cmp_lt_u32_e32 vcc, s0, v19
	v_add_u32_e32 v19, 0xffffff4d, v18
	s_nop 0
	v_cndmask_b32_e32 v58, v216, v58, vcc
	v_cmp_lt_u32_e32 vcc, s0, v19
	v_add_u32_e32 v19, 0xffffff6c, v18
	s_nop 0
	v_cndmask_b32_e32 v74, v216, v74, vcc
	v_cmp_lt_u32_e32 vcc, s0, v19
	v_add_u32_e32 v19, 0xffffff4c, v18
	s_nop 0
	v_cndmask_b32_e32 v59, v216, v59, vcc
	v_cmp_lt_u32_e32 vcc, s0, v19
	v_add_u32_e32 v19, 0xffffff67, v18
	s_nop 0
	v_cndmask_b32_e32 v75, v216, v75, vcc
	v_cmp_lt_u32_e32 vcc, s0, v19
	v_add_u32_e32 v19, 0xffffff47, v18
	s_nop 0
	v_cndmask_b32_e32 v60, v216, v60, vcc
	v_cmp_lt_u32_e32 vcc, s0, v19
	v_add_u32_e32 v19, 0xffffff66, v18
	s_nop 0
	v_cndmask_b32_e32 v76, v216, v76, vcc
	v_cmp_lt_u32_e32 vcc, s0, v19
	v_add_u32_e32 v19, 0xffffff46, v18
	s_nop 0
	v_cndmask_b32_e32 v61, v216, v61, vcc
	v_cmp_lt_u32_e32 vcc, s0, v19
	v_add_u32_e32 v19, 0xffffff65, v18
	s_nop 0
	v_cndmask_b32_e32 v77, v216, v77, vcc
	v_cmp_lt_u32_e32 vcc, s0, v19
	v_add_u32_e32 v19, 0xffffff45, v18
	s_nop 0
	v_cndmask_b32_e32 v62, v216, v62, vcc
	v_cmp_lt_u32_e32 vcc, s0, v19
	v_add_u32_e32 v19, 0xffffff64, v18
	v_add_u32_e32 v18, 0xffffff44, v18
	v_cndmask_b32_e32 v78, v216, v78, vcc
	v_cmp_lt_u32_e32 vcc, s0, v19
	s_nop 1
	v_cndmask_b32_e32 v63, v216, v63, vcc
	v_cmp_lt_u32_e32 vcc, s0, v18
	s_nop 1
	v_cndmask_b32_e32 v79, v216, v79, vcc

.LBB0_516:
	v_cvt_pk_bf16_f32 v128, v128, v129
	v_cvt_pk_bf16_f32 v129, v130, v131
	v_cvt_pk_bf16_f32 v130, v132, v133
	v_cvt_pk_bf16_f32 v131, v134, v135
	v_exp_f32_e32 v132, v52
	v_exp_f32_e32 v133, v53
	s_waitcnt lgkmcnt(7)
	v_mfma_f32_32x32x16_bf16 v[96:111], v[44:47], v[128:131], v[96:111]
	v_cvt_pk_bf16_f32 v44, v136, v137
	v_cvt_pk_bf16_f32 v45, v138, v139
	v_cvt_pk_bf16_f32 v46, v140, v141
	v_cvt_pk_bf16_f32 v47, v142, v143
	v_exp_f32_e32 v134, v54
	v_exp_f32_e32 v135, v55
	v_exp_f32_e32 v136, v56
	s_waitcnt lgkmcnt(5)
	v_mfma_f32_32x32x16_bf16 v[112:127], v[36:39], v[128:131], v[112:127]
	v_cvt_pk_bf16_f32 v36, v80, v81
	v_cvt_pk_bf16_f32 v37, v82, v83
	v_cvt_pk_bf16_f32 v38, v84, v85
	v_cvt_pk_bf16_f32 v39, v86, v87
	v_exp_f32_e32 v128, v48
	v_exp_f32_e32 v129, v49
	v_exp_f32_e32 v130, v50
	v_mfma_f32_32x32x16_bf16 v[96:111], v[40:43], v[44:47], v[96:111]
	v_exp_f32_e32 v131, v51
	v_exp_f32_e32 v137, v57
	v_exp_f32_e32 v138, v58
	v_exp_f32_e32 v139, v59
	v_exp_f32_e32 v140, v60
	v_exp_f32_e32 v141, v61
	v_exp_f32_e32 v142, v62
	s_waitcnt lgkmcnt(4)
	v_mfma_f32_32x32x16_bf16 v[112:127], v[22:25], v[44:47], v[112:127]
	v_cvt_pk_bf16_f32 v44, v88, v89
	v_cvt_pk_bf16_f32 v45, v90, v91
	v_cvt_pk_bf16_f32 v46, v92, v93
	v_cvt_pk_bf16_f32 v47, v94, v95
	v_exp_f32_e32 v143, v63
	v_exp_f32_e32 v80, v64
	v_exp_f32_e32 v81, v65
	v_exp_f32_e32 v82, v66
	s_waitcnt lgkmcnt(3)
	v_mfma_f32_32x32x16_bf16 v[96:111], v[26:29], v[36:39], v[96:111]
	v_exp_f32_e32 v83, v67
	v_exp_f32_e32 v84, v68
	v_exp_f32_e32 v85, v69
	v_exp_f32_e32 v86, v70
	v_exp_f32_e32 v87, v71
	v_exp_f32_e32 v88, v72
	v_exp_f32_e32 v89, v73
	s_waitcnt lgkmcnt(1)
	v_mfma_f32_32x32x16_bf16 v[112:127], v[18:21], v[36:39], v[112:127]
	v_exp_f32_e32 v90, v74
	v_exp_f32_e32 v91, v75
	v_exp_f32_e32 v92, v76
	v_exp_f32_e32 v93, v77
	v_exp_f32_e32 v94, v78
	v_exp_f32_e32 v95, v79
	v_mfma_f32_32x32x16_bf16 v[96:111], v[14:17], v[44:47], v[96:111]
	v_add_f32_e32 v30, v30, v31
	v_add_f32_e32 v199, v198, v30
	s_waitcnt lgkmcnt(0)
	v_mfma_f32_32x32x16_bf16 v[112:127], v[32:35], v[44:47], v[112:127]
	s_andn2_b64 vcc, exec, s[12:13]
	s_cbranch_vccnz .Lwh498
	v_add_u32_e32 v14, s28, v195
	s_waitcnt vmcnt(0)
	ds_write_b128 v14, v[184:187]
.Lwh498:
	s_and_b64 vcc, exec, s[0:1]
	s_cbranch_vccnz .Lwh500
	v_add_u32_e32 v14, s23, v195
	s_waitcnt vmcnt(0)
	ds_write_b128 v14, v[180:183] offset:18432
.Lwh500:
	s_add_i32 s7, s7, 64
	s_add_i32 s0, s21, s22
	s_cmp_lg_u32 s0, 4
	v_subrev_u32_e32 v197, 64, v197
	v_mov_b32_e32 v198, v199
	s_waitcnt lgkmcnt(0)
	s_barrier
	s_cbranch_scc0 .Lwh_exit
	s_mov_b64 s[2:3], s[14:15]
	s_mov_b32 s8, s22
	s_branch .LBB0_489
.Lwh_exit:
	s_nop 4
	v_mov_b64_e32 v[144:145], v[128:129]
	v_mov_b64_e32 v[160:161], v[80:81]
	v_mov_b64_e32 v[146:147], v[130:131]
	v_mov_b64_e32 v[148:149], v[132:133]
	v_mov_b64_e32 v[150:151], v[134:135]
	v_mov_b64_e32 v[152:153], v[136:137]
	v_mov_b64_e32 v[154:155], v[138:139]
	v_mov_b64_e32 v[156:157], v[140:141]
	v_mov_b64_e32 v[158:159], v[142:143]
	v_mov_b64_e32 v[162:163], v[82:83]
	v_mov_b64_e32 v[164:165], v[84:85]
	v_mov_b64_e32 v[166:167], v[86:87]
	v_mov_b64_e32 v[168:169], v[88:89]
	v_mov_b64_e32 v[170:171], v[90:91]
	v_mov_b64_e32 v[172:173], v[92:93]
	v_mov_b64_e32 v[174:175], v[94:95]
	v_mov_b64_e32 v[16:17], v[96:97]
	v_mov_b64_e32 v[18:19], v[98:99]
	v_mov_b64_e32 v[20:21], v[100:101]
	v_mov_b64_e32 v[22:23], v[102:103]
	v_mov_b64_e32 v[24:25], v[104:105]
	v_mov_b64_e32 v[26:27], v[106:107]
	v_mov_b64_e32 v[28:29], v[108:109]
	v_mov_b64_e32 v[32:33], v[112:113]
	v_mov_b64_e32 v[30:31], v[110:111]
	v_mov_b64_e32 v[34:35], v[114:115]
	v_mov_b64_e32 v[36:37], v[116:117]
	v_mov_b64_e32 v[38:39], v[118:119]
	v_mov_b64_e32 v[40:41], v[120:121]
	v_mov_b64_e32 v[42:43], v[122:123]
	v_mov_b64_e32 v[44:45], v[124:125]
	v_mov_b64_e32 v[46:47], v[126:127]
	s_branch .LBB0_404

.LBB0_541:
	v_exp_f32_e32 v142, v62
	v_exp_f32_e32 v145, v63
	v_exp_f32_e32 v144, v64
	v_exp_f32_e32 v146, v65
	v_exp_f32_e32 v124, v66
	v_exp_f32_e32 v128, v67
	v_exp_f32_e32 v127, v68
	v_exp_f32_e32 v134, v69
	ds_read_b128 v[34:37], v116
	ds_read_b128 v[38:41], v116 offset:32
	ds_read_b128 v[62:65], v116 offset:64
	ds_read_b128 v[66:69], v116 offset:96
	v_exp_f32_e32 v139, v58
	v_exp_f32_e32 v141, v59
	v_exp_f32_e32 v140, v60
	v_exp_f32_e32 v143, v61
	v_exp_f32_e32 v121, v42
	v_exp_f32_e32 v123, v43
	v_exp_f32_e32 v122, v44
	v_exp_f32_e32 v126, v45
	v_exp_f32_e32 v125, v46
	v_exp_f32_e32 v132, v47
	v_exp_f32_e32 v131, v48
	v_exp_f32_e32 v135, v49
	v_exp_f32_e32 v0, v50
	v_exp_f32_e32 v43, v51
	v_exp_f32_e32 v42, v52
	v_exp_f32_e32 v45, v53
	v_exp_f32_e32 v44, v54
	v_exp_f32_e32 v119, v55
	v_exp_f32_e32 v118, v56
	v_exp_f32_e32 v120, v57
	s_waitcnt lgkmcnt(3)
	v_mfma_f32_32x32x16_bf16 v[46:61], v[34:37], v[90:93], 0
	v_exp_f32_e32 v133, v70
	v_exp_f32_e32 v137, v71
	v_exp_f32_e32 v136, v72
	v_exp_f32_e32 v138, v73
	v_cvt_pk_bf16_f32 v174, v139, v141
	v_cvt_pk_bf16_f32 v175, v140, v143
	v_cvt_pk_bf16_f32 v176, v142, v145
	s_waitcnt lgkmcnt(2)
	v_mfma_f32_32x32x16_bf16 v[46:61], v[38:41], v[86:89], v[46:61]
	ds_read_b128 v[34:37], v116 offset:4608
	ds_read_b128 v[38:41], v116 offset:4640
	ds_read_b128 v[148:151], v116 offset:4672
	ds_read_b128 v[152:155], v116 offset:4704
	v_cvt_pk_bf16_f32 v177, v144, v146
	s_and_b64 vcc, exec, s[4:5]
	s_waitcnt lgkmcnt(5)
	v_mfma_f32_32x32x16_bf16 v[46:61], v[62:65], v[82:85], v[46:61]
	s_waitcnt lgkmcnt(4)
	v_mfma_f32_32x32x16_bf16 v[46:61], v[66:69], v[78:81], v[46:61]
	s_waitcnt lgkmcnt(3)
	v_mfma_f32_32x32x16_bf16 v[62:77], v[34:37], v[90:93], 0
	v_add_f32_e32 v34, v1, v139
	v_add_f32_e32 v35, v1, v141
	v_cvt_pk_bf16_f32 v141, v127, v134
	v_add_f32_e32 v34, v34, v140
	v_add_f32_e32 v35, v35, v143
	v_cvt_pk_bf16_f32 v140, v124, v128
	v_add_f32_e32 v34, v34, v142
	s_waitcnt lgkmcnt(2)
	v_mfma_f32_32x32x16_bf16 v[62:77], v[38:41], v[86:89], v[62:77]
	v_add_f32_e32 v34, v34, v144
	v_add_f32_e32 v35, v35, v145
	v_cvt_pk_bf16_f32 v142, v133, v137
	v_add_f32_e32 v34, v34, v124
	v_add_f32_e32 v35, v35, v146
	v_cvt_pk_bf16_f32 v143, v136, v138
	v_add_f32_e32 v34, v34, v127
	v_add_f32_e32 v35, v35, v128
	s_waitcnt lgkmcnt(1)
	v_mfma_f32_32x32x16_bf16 v[62:77], v[148:151], v[82:85], v[62:77]
	v_add_f32_e32 v34, v34, v133
	v_add_f32_e32 v35, v35, v134
	v_cvt_pk_bf16_f32 v139, v131, v135
	v_add_f32_e32 v34, v34, v136
	v_add_f32_e32 v35, v35, v137
	v_cvt_pk_bf16_f32 v136, v121, v123
	v_add_f32_e32 v34, v34, v121
	v_add_f32_e32 v35, v35, v138
	s_waitcnt lgkmcnt(0)
	v_mfma_f32_32x32x16_bf16 v[62:77], v[152:155], v[78:81], v[62:77]
	v_add_f32_e32 v34, v34, v122
	v_add_f32_e32 v35, v35, v123
	v_cvt_pk_bf16_f32 v137, v122, v126
	v_add_f32_e32 v34, v34, v125
	v_add_f32_e32 v35, v35, v126
	v_cvt_pk_bf16_f32 v138, v125, v132
	v_add_f32_e32 v34, v34, v131
	v_add_f32_e32 v35, v35, v132
	v_cvt_pk_bf16_f32 v122, v0, v43
	v_add_f32_e32 v34, v34, v0
	v_add_f32_e32 v35, v35, v135
	v_cvt_pk_bf16_f32 v123, v42, v45
	v_add_f32_e32 v34, v34, v42
	v_cvt_pk_bf16_f32 v124, v44, v119
	v_add_f32_e32 v34, v34, v44
	v_cvt_pk_bf16_f32 v125, v118, v120
	v_add_f32_e32 v147, v34, v118
	v_add_f32_e32 v34, v35, v43
	s_nop 0
	v_add_f32_e32 v34, v34, v45
	s_nop 0
	v_add_f32_e32 v34, v34, v119
	s_nop 0
	v_add_f32_e32 v148, v34, v120
	ds_read_b128 v[150:153], v116 offset:27648
	ds_read_b128 v[154:157], v116 offset:32256
	ds_read_b128 v[158:161], v116 offset:27680
	ds_read_b128 v[162:165], v116 offset:32288
	ds_read_b128 v[166:169], v116 offset:27712
	ds_read_b128 v[170:173], v116 offset:32320
	ds_read_b128 v[34:37], v116 offset:27744
	ds_read_b128 v[38:41], v116 offset:32352
	s_waitcnt lgkmcnt(7)
	v_mfma_f32_32x32x16_bf16 v[2:17], v[150:153], v[174:177], v[2:17]
	v_exp_f32_e32 v46, v46
	v_exp_f32_e32 v0, v62
	s_waitcnt lgkmcnt(6)
	v_mfma_f32_32x32x16_bf16 v[18:33], v[154:157], v[174:177], v[18:33]
	v_exp_f32_e32 v44, v48
	v_exp_f32_e32 v42, v50
	s_waitcnt lgkmcnt(5)
	v_mfma_f32_32x32x16_bf16 v[2:17], v[158:161], v[140:143], v[2:17]
	v_exp_f32_e32 v128, v51
	v_exp_f32_e32 v127, v53
	s_waitcnt lgkmcnt(4)
	v_mfma_f32_32x32x16_bf16 v[18:33], v[162:165], v[140:143], v[18:33]
	v_exp_f32_e32 v126, v65
	v_exp_f32_e32 v134, v54
	s_waitcnt lgkmcnt(3)
	v_mfma_f32_32x32x16_bf16 v[2:17], v[166:169], v[136:139], v[2:17]
	v_exp_f32_e32 v135, v56
	v_exp_f32_e32 v131, v59
	s_waitcnt lgkmcnt(2)
	v_mfma_f32_32x32x16_bf16 v[18:33], v[170:173], v[136:139], v[18:33]
	v_exp_f32_e32 v133, v60
	v_exp_f32_e32 v132, v61
	v_exp_f32_e32 v137, v49
	v_exp_f32_e32 v136, v58
	s_waitcnt lgkmcnt(1)
	v_mfma_f32_32x32x16_bf16 v[2:17], v[34:37], v[122:125], v[2:17]
	v_exp_f32_e32 v118, v72
	v_exp_f32_e32 v119, v73
	s_waitcnt lgkmcnt(0)
	v_mfma_f32_32x32x16_bf16 v[18:33], v[38:41], v[122:125], v[18:33]
	v_exp_f32_e32 v120, v74
	v_exp_f32_e32 v121, v75
	s_cbranch_vccnz .LBB0_543
	ds_write_b128 v111, v[98:101] offset:9216
.LBB0_543:
	v_add_f32_e32 v39, v129, v130
	v_add_f32_e32 v39, v110, v39
	v_add_f32_e32 v41, v147, v148
	v_exp_f32_e32 v37, v47
	v_exp_f32_e32 v35, v63
	v_exp_f32_e32 v40, v52
	v_exp_f32_e32 v38, v64
	v_exp_f32_e32 v34, v66
	v_exp_f32_e32 v124, v67
	v_exp_f32_e32 v36, v68
	v_exp_f32_e32 v125, v69
	v_exp_f32_e32 v129, v55
	v_exp_f32_e32 v130, v57
	v_add_f32_e32 v110, v39, v41
	v_exp_f32_e32 v39, v70
	v_exp_f32_e32 v41, v71
	v_exp_f32_e32 v122, v76
	v_exp_f32_e32 v123, v77
	s_andn2_b64 vcc, exec, s[20:21]
	s_waitcnt vmcnt(0)
	ds_write_b128 v111, v[106:109] offset:18432
	s_waitcnt lgkmcnt(0)
	s_barrier
	s_cbranch_vccz .LBB0_545
	s_mov_b32 s25, s26
	s_branch .LBB0_533
